# v15: v14 plus one static s_setprio 1 for waves 4-7 at kernel entry
# baseline (speedup 1.0000x reference)
_Z10fwd_kernelILi0ELi34EEv4Args:
	v_readfirstlane_b32 s98, v0
	s_lshr_b32 s98, s98, 8
	s_cmp_eq_u32 s98, 0
	s_cbranch_scc1 .Lstatic_prio_skip
	s_setprio 1
.Lstatic_prio_skip:
	s_mov_b64 s[84:85], s[0:1]
	s_load_dword s74, s[0:1], 0x110
	s_add_u32 s0, s84, 0x110
	s_addc_u32 s1, s85, 0
	v_readfirstlane_b32 s50, v0
	v_writelane_b32 v254, s0, 0
	v_cmp_gt_u32_e32 vcc, 64, v0
	s_nop 0
	v_writelane_b32 v254, s1, 1
	s_and_saveexec_b64 s[4:5], vcc
	v_lshl_add_u32 v1, v0, 2, 0
	v_add_u32_e32 v1, 0x24000, v1
	v_mov_b32_e32 v2, 0
	ds_write_b32 v1, v2
	s_or_b64 exec, exec, s[4:5]
	s_load_dwordx2 s[82:83], s[84:85], 0x108
	s_waitcnt lgkmcnt(0)
	s_barrier
	s_getreg_b32 s0, hwreg(HW_REG_XCC_ID, 0, 4)
	s_add_u32 s62, s82, 0x4000
	s_addc_u32 s63, s83, 0
	s_and_b32 s81, s0, 15
	v_cmp_eq_u32_e64 s[64:65], 0, v0
	v_mov_b64_e32 v[2:3], s[82:83]
	s_and_saveexec_b64 s[6:7], s[64:65]
	s_cbranch_execz .LBB0_6
	s_mov_b64 s[10:11], exec
	v_mbcnt_lo_u32_b32 v1, s10, 0
	v_mbcnt_hi_u32_b32 v1, s11, v1
	v_cmp_eq_u32_e32 vcc, 0, v1
	v_mov_b64_e32 v[2:3], s[82:83]
	s_and_saveexec_b64 s[8:9], vcc
	s_cbranch_execz .LBB0_5
	s_lshl_b32 s0, s81, 8
	s_bcnt1_i32_b64 s1, s[10:11]
	v_mov_b32_e32 v1, s0
	v_mov_b32_e32 v2, s1
	global_atomic_add v1, v2, s[62:63] offset:1024
	s_load_dwordx2 s[0:1], s[84:85], 0x108
	s_waitcnt lgkmcnt(0)
	v_mov_b64_e32 v[2:3], s[0:1]
